# phase 13: next unit's first fragment reads issued at the top of the int8-quantisation epilogue instead of at the unit header
# baseline (speedup 1.0000x reference)
; #define PG8_STAGE(bufoff, gbase, voff) do { _Pragma("unroll") for (int _i = 0; _i < 2; ++_i) \
;         __builtin_amdgcn_global_load_lds((const unsigned*)((const char*)(gbase) + (voff)[_i]), (LAS unsigned*)(lds + (bufoff) + ldsw + _i * 8192), 16, 0, 0); } while (0)
; #define PG8_LDA(dst, b, h) do { _Pragma("unroll") for (int m = 0; m < 4; ++m) _Pragma("unroll") for (int k = 0; k < 2; ++k) dst[m][k] = *(const LAS bf16x8*)(lds + PG8_SA(b, h) + aoff + m * 2048 + k * 1024); } while (0)
; #define PG8_LDB(dst, b, h) do { _Pragma("unroll") for (int n = 0; n < 2; ++n) _Pragma("unroll") for (int k = 0; k < 2; ++k) dst[n][k] = *(const LAS bf16x8*)(lds + PG8_SB(b, h) + boff + n * 2048 + k * 1024); } while (0)
; #define PG8_WAIT_V(n) asm volatile("s_waitcnt vmcnt(" #n ")" ::: "memory")
; #define PG8_BAR __builtin_amdgcn_s_barrier()
; #define PG8_SCHED __builtin_amdgcn_sched_barrier(0)
;     ...
;     PG8_STAGE(PG8_SB(0, 0), cB, voffB); PG8_STAGE(PG8_SB(0, 1), cB + hstep, voffB); PG8_STAGE(PG8_SA(0, 0), cA, voffA); PG8_STAGE(PG8_SA(0, 1), cA + hstep, voffA);
;     if (wr == 1) PG8_BAR;
;     PG8_WAIT_V(2); PG8_BAR;
;     PG8_STAGE(PG8_SB(1, 0), cB + kstep, voffB); PG8_STAGE(PG8_SA(1, 0), cA + kstep, voffA); PG8_STAGE(PG8_SB(1, 1), cB + hstep + kstep, voffB);
;     PG8_WAIT_V(6); PG8_BAR;
;     ...
;             PG8_LDB(B0, 0, 0); PG8_LDB(B1, 0, 1); PG8_SCHED; PG8_LDA(At, 0, 0); PG8_STAGE(PG8_SA(1, 1), a1 + hstep, voffA);
.LBB0_4803:
	s_add_u32 s16, s56, 0x5a000000
	s_mov_b64 s[18:19], 0x80
	s_addc_u32 s17, s57, 0
	s_add_i32 m0, s44, 0x18000
	v_lshl_add_u64 v[8:9], v[8:9], 0, s[18:19]
	s_waitcnt vmcnt(2)
	s_barrier
	global_load_lds_dwordx4 v[8:9], off
	v_lshl_add_u64 v[6:7], v[6:7], 0, s[18:19]
	s_add_i32 m0, s44, 0x1a000
	s_add_i32 s48, s44, 0x8000
	global_load_lds_dwordx4 v[6:7], off
	v_lshl_add_u64 v[2:3], v[2:3], 0, s[18:19]
	s_mov_b32 m0, s48
	s_add_i32 s49, s44, 0xa000
	global_load_lds_dwordx4 v[2:3], off
	v_lshl_add_u64 v[2:3], v[4:5], 0, s[18:19]
	s_mov_b32 m0, s49
	s_mov_b64 s[20:21], 0xe0080
	global_load_lds_dwordx4 v[2:3], off
	v_lshl_add_u64 v[2:3], v[0:1], 0, s[20:21]
	s_add_i32 m0, s44, 0x1c000
	v_lshl_add_u64 v[4:5], v[2:3], 0, v[160:161]
	global_load_lds_dwordx4 v[4:5], off
	v_lshl_add_u64 v[2:3], v[2:3], 0, v[166:167]
	s_add_i32 m0, s44, 0x1e000
	s_mov_b32 s27, 0xe000
	global_load_lds_dwordx4 v[2:3], off
	v_lshrrev_b32_e32 v3, 1, v10
	v_and_b32_e32 v3, 24, v3
	v_and_b32_e32 v2, 15, v10
	v_lshlrev_b32_e32 v4, 1, v3
	v_lshl_or_b32 v190, s4, 6, v2
	v_lshl_or_b32 v2, v2, 6, v4
	v_lshlrev_b32_e32 v4, 2, v10
	s_lshl_b32 s4, s4, 13
	v_and_b32_e32 v4, 32, v4
	v_bitop3_b32 v5, v2, s4, v4 bitop3:0xde
	s_lshl_b32 s4, s5, 5
	s_and_b32 s4, s4, 0x60
	s_lshl_b32 s5, s4, 7
	v_bitop3_b32 v191, s5, v2, v4 bitop3:0xf6
	v_or_b32_e32 v192, s4, v3
	v_lshrrev_b32_e32 v3, 1, v13
	v_mul_lo_u32 v2, v15, s26
	v_mad_u64_u32 v[2:3], s[4:5], v3, s27, v[2:3]
	v_or_b32_e32 v2, v2, v14
	v_add_lshl_u32 v168, v2, v17, 1
	v_lshrrev_b32_e32 v3, 1, v11
	v_mul_lo_u32 v2, v16, s26
	v_mad_u64_u32 v[2:3], s[4:5], v3, s27, v[2:3]
	s_waitcnt vmcnt(6)
	s_cmpk_lt_u32 s3, 0x100
	v_mov_b32_e32 v169, 0
	v_or_b32_e32 v2, v2, v12
	s_cselect_b64 s[24:25], -1, 0
	s_ashr_i32 s3, s2, 31
	v_lshl_add_u64 v[170:171], v[168:169], 0, s[20:21]
	v_add_lshl_u32 v168, v2, v18, 1
	s_add_i32 s54, 0, 0x10000
	s_add_i32 s55, 0, 0x14000
	s_mov_b32 s50, 0
	s_ashr_i32 s51, s33, 31
	v_lshl_add_u64 v[172:173], v[168:169], 0, s[20:21]
	v_mov_b64_e32 v[174:175], s[2:3]
	s_mov_b64 s[26:27], 0x100
	v_add_u32_e32 v168, s54, v191
	v_add_u32_e32 v193, s55, v191
	v_add_u32_e32 v194, 0, v5
	v_mov_b32_e32 v195, 0x7f7f7f7f
	s_mov_b32 s28, 0x3cc80000
	s_mov_b32 s58, 0xc2fe0000
	s_mov_b32 s59, 0xc0c0400
	s_mov_b32 s60, 0x4000c0c
	s_mov_b32 s61, 0x80808080
	v_mov_b32_e32 v196, 0x42fe0000
	v_mov_b32_e32 v247, 0x4b400000
	v_mov_b32_e32 v248, 0x4b40007f
	s_mov_b32 s32, 0x4b3fff81
	s_barrier
	ds_read_b128 v[24:27], v168
	ds_read_b128 v[28:31], v168 offset:1024
	ds_read_b128 v[16:19], v168 offset:2048
	ds_read_b128 v[20:23], v168 offset:3072
	ds_read_b128 v[182:185], v194
	ds_read_b128 v[186:189], v194 offset:1024
	ds_read_b128 v[198:201], v194 offset:2048
	ds_read_b128 v[202:205], v194 offset:3072
	ds_read_b128 v[206:209], v194 offset:4096
	ds_read_b128 v[210:213], v194 offset:5120
	ds_read_b128 v[214:217], v194 offset:6144
	ds_read_b128 v[218:221], v194 offset:7168
	s_branch .LBB0_4806

;     __device__ __forceinline__ bool next(int i, Unit& u) const {
;         const long L = (long)i * G + c; if (L >= nwg) return false;
;         int wgid = (int)L; { const int q = nwg / NXCD, r = nwg % NXCD, xcd = wgid % NXCD, off = wgid / NXCD; wgid = (xcd < r ? xcd * (q + 1) : r * (q + 1) + (xcd - r) * q) + off; }
;         const int nig = WGM * nN, gid = wgid / nig, fm = gid * WGM, gsz = (nM - fm) < WGM ? (nM - fm) : WGM;
;         u.pm = fm + ((wgid % nig) % gsz); u.pn = (wgid % nig) / gsz; u.e = 0; u.kt0 = 0; u.nkt = nt; u.buf = 0;
;         if (ts) { int e = 0;
; #pragma unroll
;             for (int j = 1; j < 8; ++j) e += (u.pm >= ts[j]) ? 1 : 0;
;             u.e = e; }
;     ...
;         const bool has_next = S.next(ui + 1, nxt);
.LBB0_4806:
	ds_read_b128 v[12:15], v193 offset:1024
	s_add_i32 s50, s50, 1
	s_mul_i32 s2, s50, s51
	s_mul_hi_u32 s3, s50, s33
	s_add_i32 s3, s3, s2
	s_mul_i32 s2, s50, s33
	s_add_u32 s2, s2, s22
	s_addc_u32 s3, s3, s41
	v_cmp_ge_i64_e32 vcc, s[2:3], v[174:175]
	v_cmp_lt_i64_e64 s[4:5], s[2:3], v[174:175]
	s_cbranch_vccnz .LBB0_4808
	s_ashr_i32 s3, s2, 31
	s_lshr_b32 s3, s3, 29
	s_add_i32 s3, s2, s3
	s_ashr_i32 s36, s3, 3
	s_and_b32 s3, s3, -8
	s_sub_i32 s2, s2, s3
	s_lshr_b32 s3, s2, 31
	s_add_i32 s3, s23, s3
	s_mul_i32 s2, s3, s2
	s_add_i32 s2, s2, s36
	s_ashr_i32 s3, s2, 31
	s_lshr_b32 s3, s3, 26
	s_add_i32 s3, s2, s3
	s_ashr_i32 s36, s3, 6
	s_lshl_b32 s36, s36, 3
	s_sub_i32 s37, s23, s36
	s_min_i32 s37, s37, 8
	s_abs_i32 s38, s37
	v_cvt_f32_u32_e32 v9, s38
	s_sub_i32 s62, 0, s38
	s_andn2_b32 s3, s3, 63
	s_sub_i32 s2, s2, s3
	v_rcp_iflag_f32_e32 v9, v9
	s_abs_i32 s3, s2
	s_xor_b32 s39, s2, s37
	s_ashr_i32 s39, s39, 31
	v_mul_f32_e32 v9, 0x4f7ffffe, v9
	v_cvt_u32_f32_e32 v9, v9
	s_nop 0
	v_readfirstlane_b32 s63, v9
	s_mul_i32 s62, s62, s63
	s_mul_hi_u32 s62, s63, s62
	s_add_i32 s63, s63, s62
	s_mul_hi_u32 s62, s3, s63
	s_mul_i32 s63, s62, s38
	s_sub_i32 s3, s3, s63
	s_add_i32 s66, s62, 1
	s_sub_i32 s63, s3, s38
	s_cmp_ge_u32 s3, s38
	s_cselect_b32 s62, s66, s62
	s_cselect_b32 s3, s63, s3
	s_add_i32 s63, s62, 1
	s_cmp_ge_u32 s3, s38
	s_cselect_b32 s3, s63, s62
	s_xor_b32 s3, s3, s39
	s_sub_i32 s62, s3, s39
	s_mul_i32 s3, s62, s37
	s_sub_i32 s2, s2, s3
	s_add_i32 s63, s2, s36
	v_cmp_ge_i32_e32 vcc, s63, v240
	s_nop 1
	v_cndmask_b32_e64 v2, 0, 1, vcc
	v_cmp_ge_i32_e32 vcc, s63, v241
	s_nop 1
	v_cndmask_b32_e64 v3, 0, 1, vcc
	v_cmp_ge_i32_e32 vcc, s63, v243
	s_nop 1
	v_cndmask_b32_e64 v5, 0, 1, vcc
	v_cmp_ge_i32_e32 vcc, s63, v245
	s_nop 1
	v_cndmask_b32_e64 v7, 0, 1, vcc
	v_cmp_ge_i32_e32 vcc, s63, v242
	s_nop 1
	v_addc_co_u32_e32 v2, vcc, v3, v2, vcc
	v_cmp_ge_i32_e32 vcc, s63, v244
	s_nop 1
	v_addc_co_u32_e32 v2, vcc, v2, v5, vcc
	v_cmp_ge_i32_e32 vcc, s63, v246
	s_nop 1
	v_addc_co_u32_e32 v197, vcc, v2, v7, vcc

; __device__ __forceinline__ u32x2 pack8i8(const f32x4 a, const f32x4 b) { return (u32x2){pack4i8(a), pack4i8(b)}; }
; __device__ __forceinline__ unsigned pack4i8(const f32x4 t) {
;     const float M = 12582912.f; const unsigned a = __float_as_uint(__builtin_amdgcn_fmed3f(t[0], -127.f, 127.f) + M), b = __float_as_uint(__builtin_amdgcn_fmed3f(t[1], -127.f, 127.f) + M),
;                    c = __float_as_uint(__builtin_amdgcn_fmed3f(t[2], -127.f, 127.f) + M), d = __float_as_uint(__builtin_amdgcn_fmed3f(t[3], -127.f, 127.f) + M);
;     return __builtin_amdgcn_perm(b, a, 0x0c0c0400u) | __builtin_amdgcn_perm(d, c, 0x04000c0cu); }
;     __device__ __forceinline__ void operator()(EPI_ARGS) const {
;     ...
;             for (int m = 0; m < 4; ++m) { const size_t eo = (size_t)u.buf * bufstride + (size_t)(row0 - rowoff + ai * HALF + m * 16) * ldc + col0;
;                 if (f8 < 0.f) { const float s8 = ascale * -f8;
; #pragma unroll
;                     for (int bj = 0; bj < 2; ++bj) { u32x2 w = pack8i8(acc[ai][bj][m][0] * s8, acc[ai][bj][m][1] * s8); w.x ^= 0x80808080u; w.y ^= 0x80808080u; *(u32x2*)((unsigned char*)O + eo + bj * HALF) = w; } }
.LBB0_4816:
	ds_read_b128 v[24:27], v168
	ds_read_b128 v[28:31], v168 offset:1024
	ds_read_b128 v[16:19], v168 offset:2048
	ds_read_b128 v[20:23], v168 offset:3072
	ds_read_b128 v[182:185], v194
	ds_read_b128 v[186:189], v194 offset:1024
	ds_read_b128 v[198:201], v194 offset:2048
	ds_read_b128 v[202:205], v194 offset:3072
	ds_read_b128 v[206:209], v194 offset:4096
	ds_read_b128 v[210:213], v194 offset:5120
	ds_read_b128 v[214:217], v194 offset:6144
	ds_read_b128 v[218:221], v194 offset:7168
	v_lshl_add_u32 v2, s65, 8, v190
	v_ashrrev_i32_e32 v3, 31, v2
	v_fmamk_f32 v6, v158, 0x3cc80000, v247
	v_fmamk_f32 v7, v159, 0x3cc80000, v247
	v_fmamk_f32 v8, v156, 0x3cc80000, v247
	v_fmamk_f32 v9, v157, 0x3cc80000, v247
	v_lshlrev_b64 v[4:5], 11, v[2:3]
	v_med3_f32 v3, v8, s32, v248
	v_med3_f32 v8, v9, s32, v248
	v_med3_f32 v6, v6, s32, v248
	v_med3_f32 v7, v7, s32, v248
	v_fmamk_f32 v10, v154, 0x3cc80000, v247
	v_fmamk_f32 v11, v155, 0x3cc80000, v247
	v_fmamk_f32 v12, v152, 0x3cc80000, v247
	v_fmamk_f32 v13, v153, 0x3cc80000, v247
	v_perm_b32 v3, v8, v3, s59
	v_perm_b32 v6, v7, v6, s60
	v_med3_f32 v7, v12, s32, v248
	v_med3_f32 v8, v13, s32, v248
	v_med3_f32 v9, v10, s32, v248
	v_med3_f32 v10, v11, s32, v248
	v_lshl_or_b32 v0, s64, 8, v192
	v_ashrrev_i32_e32 v1, 31, v0
	v_perm_b32 v7, v8, v7, s59
	v_perm_b32 v8, v10, v9, s60
	v_lshl_add_u64 v[4:5], s[16:17], 0, v[4:5]
	v_bitop3_b32 v6, v3, s61, v6 bitop3:0x36
	v_bitop3_b32 v7, v7, s61, v8 bitop3:0x36
	v_lshl_add_u64 v[4:5], v[4:5], 0, v[0:1]
	global_store_dwordx2 v[4:5], v[6:7], off
	v_fmamk_f32 v6, v150, 0x3cc80000, v247
	v_fmamk_f32 v7, v151, 0x3cc80000, v247
	v_fmamk_f32 v8, v148, 0x3cc80000, v247
	v_fmamk_f32 v9, v149, 0x3cc80000, v247
	v_med3_f32 v6, v6, s32, v248
	v_med3_f32 v3, v8, s32, v248
	v_med3_f32 v8, v9, s32, v248
	v_med3_f32 v7, v7, s32, v248
	v_fmamk_f32 v10, v146, 0x3cc80000, v247
	v_fmamk_f32 v11, v147, 0x3cc80000, v247
	v_fmamk_f32 v12, v144, 0x3cc80000, v247
	v_fmamk_f32 v13, v145, 0x3cc80000, v247
	v_perm_b32 v3, v8, v3, s59
	v_perm_b32 v6, v7, v6, s60
	v_med3_f32 v7, v12, s32, v248
	v_med3_f32 v8, v13, s32, v248
	v_med3_f32 v9, v10, s32, v248
	v_med3_f32 v10, v11, s32, v248
	v_perm_b32 v7, v8, v7, s59
	v_perm_b32 v8, v10, v9, s60
	v_bitop3_b32 v6, v3, s61, v6 bitop3:0x36
	v_bitop3_b32 v7, v7, s61, v8 bitop3:0x36
	global_store_dwordx2 v[4:5], v[6:7], off offset:128
	v_fmamk_f32 v6, v142, 0x3cc80000, v247
	v_fmamk_f32 v7, v143, 0x3cc80000, v247
	v_fmamk_f32 v8, v140, 0x3cc80000, v247
	v_fmamk_f32 v9, v141, 0x3cc80000, v247
	v_med3_f32 v6, v6, s32, v248
	v_med3_f32 v3, v8, s32, v248
	v_med3_f32 v8, v9, s32, v248
	v_med3_f32 v7, v7, s32, v248
	v_or_b32_e32 v4, 16, v2
	v_fmamk_f32 v10, v138, 0x3cc80000, v247
	v_fmamk_f32 v11, v139, 0x3cc80000, v247
	v_fmamk_f32 v12, v136, 0x3cc80000, v247
	v_fmamk_f32 v13, v137, 0x3cc80000, v247
	v_ashrrev_i32_e32 v5, 31, v4
	v_perm_b32 v3, v8, v3, s59
	v_perm_b32 v6, v7, v6, s60
	v_med3_f32 v7, v12, s32, v248
	v_med3_f32 v8, v13, s32, v248
	v_med3_f32 v9, v10, s32, v248
	v_med3_f32 v10, v11, s32, v248
	v_lshlrev_b64 v[4:5], 11, v[4:5]
	v_perm_b32 v7, v8, v7, s59
	v_perm_b32 v8, v10, v9, s60
	v_lshl_add_u64 v[4:5], s[16:17], 0, v[4:5]
	v_bitop3_b32 v6, v3, s61, v6 bitop3:0x36
	v_bitop3_b32 v7, v7, s61, v8 bitop3:0x36
	v_lshl_add_u64 v[4:5], v[4:5], 0, v[0:1]
	global_store_dwordx2 v[4:5], v[6:7], off
	v_fmamk_f32 v6, v134, 0x3cc80000, v247
	v_fmamk_f32 v7, v135, 0x3cc80000, v247
	v_fmamk_f32 v8, v132, 0x3cc80000, v247
	v_fmamk_f32 v9, v133, 0x3cc80000, v247
	v_med3_f32 v6, v6, s32, v248
	v_med3_f32 v3, v8, s32, v248
	v_med3_f32 v8, v9, s32, v248
	v_med3_f32 v7, v7, s32, v248
	v_fmamk_f32 v10, v130, 0x3cc80000, v247
	v_fmamk_f32 v11, v131, 0x3cc80000, v247
	v_fmamk_f32 v12, v128, 0x3cc80000, v247
	v_fmamk_f32 v13, v129, 0x3cc80000, v247
	v_perm_b32 v3, v8, v3, s59
	v_perm_b32 v6, v7, v6, s60
	v_med3_f32 v7, v12, s32, v248
	v_med3_f32 v8, v13, s32, v248
	v_med3_f32 v9, v10, s32, v248
	v_med3_f32 v10, v11, s32, v248
	v_perm_b32 v7, v8, v7, s59
	v_perm_b32 v8, v10, v9, s60
	v_bitop3_b32 v6, v3, s61, v6 bitop3:0x36
	v_bitop3_b32 v7, v7, s61, v8 bitop3:0x36
	global_store_dwordx2 v[4:5], v[6:7], off offset:128
	v_fmamk_f32 v6, v126, 0x3cc80000, v247
	v_fmamk_f32 v7, v127, 0x3cc80000, v247
	v_fmamk_f32 v8, v124, 0x3cc80000, v247
	v_fmamk_f32 v9, v125, 0x3cc80000, v247
	v_med3_f32 v6, v6, s32, v248
	v_med3_f32 v3, v8, s32, v248
	v_med3_f32 v8, v9, s32, v248
	v_med3_f32 v7, v7, s32, v248
	v_or_b32_e32 v4, 32, v2
	v_fmamk_f32 v10, v122, 0x3cc80000, v247
	v_fmamk_f32 v11, v123, 0x3cc80000, v247
	v_fmamk_f32 v12, v120, 0x3cc80000, v247
	v_fmamk_f32 v13, v121, 0x3cc80000, v247
	v_ashrrev_i32_e32 v5, 31, v4
	v_perm_b32 v3, v8, v3, s59
	v_perm_b32 v6, v7, v6, s60
	v_med3_f32 v7, v12, s32, v248
	v_med3_f32 v8, v13, s32, v248
	v_med3_f32 v9, v10, s32, v248
	v_med3_f32 v10, v11, s32, v248
	v_lshlrev_b64 v[4:5], 11, v[4:5]
	v_perm_b32 v7, v8, v7, s59
	v_perm_b32 v8, v10, v9, s60
	v_lshl_add_u64 v[4:5], s[16:17], 0, v[4:5]
	v_bitop3_b32 v6, v3, s61, v6 bitop3:0x36
	v_bitop3_b32 v7, v7, s61, v8 bitop3:0x36
	v_lshl_add_u64 v[4:5], v[4:5], 0, v[0:1]
	global_store_dwordx2 v[4:5], v[6:7], off
	v_fmamk_f32 v6, v118, 0x3cc80000, v247
	v_fmamk_f32 v7, v119, 0x3cc80000, v247
	v_fmamk_f32 v8, v116, 0x3cc80000, v247
	v_fmamk_f32 v9, v117, 0x3cc80000, v247
	v_med3_f32 v6, v6, s32, v248
	v_med3_f32 v3, v8, s32, v248
	v_med3_f32 v8, v9, s32, v248
	v_med3_f32 v7, v7, s32, v248
	v_fmamk_f32 v10, v114, 0x3cc80000, v247
	v_fmamk_f32 v11, v115, 0x3cc80000, v247
	v_fmamk_f32 v12, v112, 0x3cc80000, v247
	v_fmamk_f32 v13, v113, 0x3cc80000, v247
	v_perm_b32 v3, v8, v3, s59
	v_perm_b32 v6, v7, v6, s60
; __device__ __forceinline__ u32x2 pack8i8(const f32x4 a, const f32x4 b) { return (u32x2){pack4i8(a), pack4i8(b)}; }
;     __device__ __forceinline__ void operator()(EPI_ARGS) const {
;     ...
;             for (int m = 0; m < 4; ++m) { const size_t eo = (size_t)u.buf * bufstride + (size_t)(row0 - rowoff + ai * HALF + m * 16) * ldc + col0;
;                 if (f8 < 0.f) { const float s8 = ascale * -f8;
; #pragma unroll
;                     for (int bj = 0; bj < 2; ++bj) { u32x2 w = pack8i8(acc[ai][bj][m][0] * s8, acc[ai][bj][m][1] * s8); w.x ^= 0x80808080u; w.y ^= 0x80808080u; *(u32x2*)((unsigned char*)O + eo + bj * HALF) = w; } }
	v_med3_f32 v7, v12, s32, v248
	v_med3_f32 v8, v13, s32, v248
	v_med3_f32 v9, v10, s32, v248
	v_med3_f32 v10, v11, s32, v248
	v_perm_b32 v7, v8, v7, s59
	v_perm_b32 v8, v10, v9, s60
	v_bitop3_b32 v6, v3, s61, v6 bitop3:0x36
	v_bitop3_b32 v7, v7, s61, v8 bitop3:0x36
	global_store_dwordx2 v[4:5], v[6:7], off offset:128
	v_fmamk_f32 v6, v110, 0x3cc80000, v247
	v_fmamk_f32 v7, v111, 0x3cc80000, v247
	v_fmamk_f32 v8, v108, 0x3cc80000, v247
	v_fmamk_f32 v9, v109, 0x3cc80000, v247
	v_med3_f32 v6, v6, s32, v248
	v_med3_f32 v3, v8, s32, v248
	v_med3_f32 v8, v9, s32, v248
	v_med3_f32 v7, v7, s32, v248
	v_or_b32_e32 v4, 48, v2
	v_fmamk_f32 v10, v106, 0x3cc80000, v247
	v_fmamk_f32 v11, v107, 0x3cc80000, v247
	v_fmamk_f32 v12, v104, 0x3cc80000, v247
	v_fmamk_f32 v13, v105, 0x3cc80000, v247
	v_ashrrev_i32_e32 v5, 31, v4
	v_perm_b32 v3, v8, v3, s59
	v_perm_b32 v6, v7, v6, s60
	v_med3_f32 v7, v12, s32, v248
	v_med3_f32 v8, v13, s32, v248
	v_med3_f32 v9, v10, s32, v248
	v_med3_f32 v10, v11, s32, v248
	v_lshlrev_b64 v[4:5], 11, v[4:5]
	v_perm_b32 v7, v8, v7, s59
	v_perm_b32 v8, v10, v9, s60
	v_lshl_add_u64 v[4:5], s[16:17], 0, v[4:5]
	v_bitop3_b32 v6, v3, s61, v6 bitop3:0x36
	v_bitop3_b32 v7, v7, s61, v8 bitop3:0x36
	v_lshl_add_u64 v[4:5], v[4:5], 0, v[0:1]
	global_store_dwordx2 v[4:5], v[6:7], off
	v_fmamk_f32 v6, v102, 0x3cc80000, v247
	v_fmamk_f32 v7, v103, 0x3cc80000, v247
	v_fmamk_f32 v8, v100, 0x3cc80000, v247
	v_fmamk_f32 v9, v101, 0x3cc80000, v247
	v_med3_f32 v6, v6, s32, v248
	v_med3_f32 v3, v8, s32, v248
	v_med3_f32 v8, v9, s32, v248
	v_med3_f32 v7, v7, s32, v248
	v_fmamk_f32 v10, v98, 0x3cc80000, v247
	v_fmamk_f32 v11, v99, 0x3cc80000, v247
	v_fmamk_f32 v12, v96, 0x3cc80000, v247
	v_fmamk_f32 v13, v97, 0x3cc80000, v247
	v_perm_b32 v3, v8, v3, s59
	v_perm_b32 v6, v7, v6, s60
	v_med3_f32 v7, v12, s32, v248
	v_med3_f32 v8, v13, s32, v248
	v_med3_f32 v9, v10, s32, v248
	v_med3_f32 v10, v11, s32, v248
	v_perm_b32 v7, v8, v7, s59
	v_perm_b32 v8, v10, v9, s60
	v_bitop3_b32 v6, v3, s61, v6 bitop3:0x36
	v_bitop3_b32 v7, v7, s61, v8 bitop3:0x36
	global_store_dwordx2 v[4:5], v[6:7], off offset:128
	v_fmamk_f32 v6, v94, 0x3cc80000, v247
	v_fmamk_f32 v7, v95, 0x3cc80000, v247
	v_fmamk_f32 v8, v92, 0x3cc80000, v247
	v_fmamk_f32 v9, v93, 0x3cc80000, v247
	v_med3_f32 v6, v6, s32, v248
	v_med3_f32 v3, v8, s32, v248
	v_med3_f32 v8, v9, s32, v248
	v_med3_f32 v7, v7, s32, v248
	v_add_u32_e32 v4, 0x80, v2
	v_fmamk_f32 v10, v90, 0x3cc80000, v247
	v_fmamk_f32 v11, v91, 0x3cc80000, v247
	v_fmamk_f32 v12, v88, 0x3cc80000, v247
	v_fmamk_f32 v13, v89, 0x3cc80000, v247
	v_ashrrev_i32_e32 v5, 31, v4
	v_perm_b32 v3, v8, v3, s59
	v_perm_b32 v6, v7, v6, s60
	v_med3_f32 v7, v12, s32, v248
	v_med3_f32 v8, v13, s32, v248
	v_med3_f32 v9, v10, s32, v248
	v_med3_f32 v10, v11, s32, v248
	v_lshlrev_b64 v[4:5], 11, v[4:5]
	v_perm_b32 v7, v8, v7, s59
	v_perm_b32 v8, v10, v9, s60
	v_lshl_add_u64 v[4:5], s[16:17], 0, v[4:5]
	v_bitop3_b32 v6, v3, s61, v6 bitop3:0x36
	v_bitop3_b32 v7, v7, s61, v8 bitop3:0x36
	v_lshl_add_u64 v[4:5], v[4:5], 0, v[0:1]
	global_store_dwordx2 v[4:5], v[6:7], off
	v_fmamk_f32 v6, v86, 0x3cc80000, v247
	v_fmamk_f32 v7, v87, 0x3cc80000, v247
	v_fmamk_f32 v8, v84, 0x3cc80000, v247
	v_fmamk_f32 v9, v85, 0x3cc80000, v247
	v_med3_f32 v6, v6, s32, v248
	v_med3_f32 v3, v8, s32, v248
	v_med3_f32 v8, v9, s32, v248
	v_med3_f32 v7, v7, s32, v248
	v_fmamk_f32 v10, v82, 0x3cc80000, v247
	v_fmamk_f32 v11, v83, 0x3cc80000, v247
	v_fmamk_f32 v12, v80, 0x3cc80000, v247
	v_fmamk_f32 v13, v81, 0x3cc80000, v247
	v_perm_b32 v3, v8, v3, s59
	v_perm_b32 v6, v7, v6, s60
	v_med3_f32 v7, v12, s32, v248
	v_med3_f32 v8, v13, s32, v248
	v_med3_f32 v9, v10, s32, v248
	v_med3_f32 v10, v11, s32, v248
	v_perm_b32 v7, v8, v7, s59
	v_perm_b32 v8, v10, v9, s60
	v_bitop3_b32 v6, v3, s61, v6 bitop3:0x36
	v_bitop3_b32 v7, v7, s61, v8 bitop3:0x36
	global_store_dwordx2 v[4:5], v[6:7], off offset:128
	v_fmamk_f32 v6, v78, 0x3cc80000, v247
	v_fmamk_f32 v7, v79, 0x3cc80000, v247
	v_fmamk_f32 v8, v76, 0x3cc80000, v247
	v_fmamk_f32 v9, v77, 0x3cc80000, v247
	v_med3_f32 v6, v6, s32, v248
	v_med3_f32 v3, v8, s32, v248
	v_med3_f32 v8, v9, s32, v248
	v_med3_f32 v7, v7, s32, v248
	v_add_u32_e32 v4, 0x90, v2
	v_fmamk_f32 v10, v74, 0x3cc80000, v247
	v_fmamk_f32 v11, v75, 0x3cc80000, v247
	v_fmamk_f32 v12, v72, 0x3cc80000, v247
	v_fmamk_f32 v13, v73, 0x3cc80000, v247
	v_ashrrev_i32_e32 v5, 31, v4
	v_perm_b32 v3, v8, v3, s59
	v_perm_b32 v6, v7, v6, s60
	v_med3_f32 v7, v12, s32, v248
	v_med3_f32 v8, v13, s32, v248
	v_med3_f32 v9, v10, s32, v248
	v_med3_f32 v10, v11, s32, v248
	v_lshlrev_b64 v[4:5], 11, v[4:5]
	v_perm_b32 v7, v8, v7, s59
	v_perm_b32 v8, v10, v9, s60
	v_lshl_add_u64 v[4:5], s[16:17], 0, v[4:5]
; #define PG8_BAR __builtin_amdgcn_s_barrier()
; __device__ __forceinline__ u32x2 pack8i8(const f32x4 a, const f32x4 b) { return (u32x2){pack4i8(a), pack4i8(b)}; }
;     ...
;         if (!has_next) break;
; #pragma unroll
;         for (int a = 0; a < 2; ++a)
; #pragma unroll
;             for (int b = 0; b < 2; ++b)
; #pragma unroll
;                 for (int m = 0; m < 4; ++m)
; #pragma unroll
;                     for (int n = 0; n < 2; ++n) acc[a][b][m][n] = (f32x4){0.f, 0.f, 0.f, 0.f};
;         cur = nxt; cA = nA; cB = nB; ++ui;
;         if (wr == 1) PG8_BAR;
;     __device__ __forceinline__ void operator()(EPI_ARGS) const {
;     ...
;             for (int m = 0; m < 4; ++m) { const size_t eo = (size_t)u.buf * bufstride + (size_t)(row0 - rowoff + ai * HALF + m * 16) * ldc + col0;
;                 if (f8 < 0.f) { const float s8 = ascale * -f8;
; #pragma unroll
;                     for (int bj = 0; bj < 2; ++bj) { u32x2 w = pack8i8(acc[ai][bj][m][0] * s8, acc[ai][bj][m][1] * s8); w.x ^= 0x80808080u; w.y ^= 0x80808080u; *(u32x2*)((unsigned char*)O + eo + bj * HALF) = w; } }
	v_bitop3_b32 v6, v3, s61, v6 bitop3:0x36
	v_bitop3_b32 v7, v7, s61, v8 bitop3:0x36
	v_lshl_add_u64 v[4:5], v[4:5], 0, v[0:1]
	global_store_dwordx2 v[4:5], v[6:7], off
	v_fmamk_f32 v6, v70, 0x3cc80000, v247
	v_fmamk_f32 v7, v71, 0x3cc80000, v247
	v_fmamk_f32 v8, v68, 0x3cc80000, v247
	v_fmamk_f32 v9, v69, 0x3cc80000, v247
	v_med3_f32 v6, v6, s32, v248
	v_med3_f32 v3, v8, s32, v248
	v_med3_f32 v8, v9, s32, v248
	v_med3_f32 v7, v7, s32, v248
	v_fmamk_f32 v10, v66, 0x3cc80000, v247
	v_fmamk_f32 v11, v67, 0x3cc80000, v247
	v_fmamk_f32 v12, v64, 0x3cc80000, v247
	v_fmamk_f32 v13, v65, 0x3cc80000, v247
	v_perm_b32 v3, v8, v3, s59
	v_perm_b32 v6, v7, v6, s60
	v_med3_f32 v7, v12, s32, v248
	v_med3_f32 v8, v13, s32, v248
	v_med3_f32 v9, v10, s32, v248
	v_med3_f32 v10, v11, s32, v248
	v_perm_b32 v7, v8, v7, s59
	v_perm_b32 v8, v10, v9, s60
	v_bitop3_b32 v6, v3, s61, v6 bitop3:0x36
	v_bitop3_b32 v7, v7, s61, v8 bitop3:0x36
	global_store_dwordx2 v[4:5], v[6:7], off offset:128
	v_fmamk_f32 v6, v62, 0x3cc80000, v247
	v_fmamk_f32 v7, v63, 0x3cc80000, v247
	v_fmamk_f32 v8, v60, 0x3cc80000, v247
	v_fmamk_f32 v9, v61, 0x3cc80000, v247
	v_med3_f32 v6, v6, s32, v248
	v_med3_f32 v3, v8, s32, v248
	v_med3_f32 v8, v9, s32, v248
	v_med3_f32 v7, v7, s32, v248
	v_add_u32_e32 v4, 0xa0, v2
	v_fmamk_f32 v10, v58, 0x3cc80000, v247
	v_fmamk_f32 v11, v59, 0x3cc80000, v247
	v_fmamk_f32 v12, v56, 0x3cc80000, v247
	v_fmamk_f32 v13, v57, 0x3cc80000, v247
	v_ashrrev_i32_e32 v5, 31, v4
	v_perm_b32 v3, v8, v3, s59
	v_perm_b32 v6, v7, v6, s60
	v_med3_f32 v7, v12, s32, v248
	v_med3_f32 v8, v13, s32, v248
	v_med3_f32 v9, v10, s32, v248
	v_med3_f32 v10, v11, s32, v248
	v_lshlrev_b64 v[4:5], 11, v[4:5]
	v_perm_b32 v7, v8, v7, s59
	v_perm_b32 v8, v10, v9, s60
	v_lshl_add_u64 v[4:5], s[16:17], 0, v[4:5]
	v_bitop3_b32 v6, v3, s61, v6 bitop3:0x36
	v_bitop3_b32 v7, v7, s61, v8 bitop3:0x36
	v_lshl_add_u64 v[4:5], v[4:5], 0, v[0:1]
	global_store_dwordx2 v[4:5], v[6:7], off
	v_fmamk_f32 v6, v54, 0x3cc80000, v247
	v_fmamk_f32 v7, v55, 0x3cc80000, v247
	v_fmamk_f32 v8, v52, 0x3cc80000, v247
	v_fmamk_f32 v9, v53, 0x3cc80000, v247
	v_med3_f32 v6, v6, s32, v248
	v_med3_f32 v3, v8, s32, v248
	v_med3_f32 v8, v9, s32, v248
	v_med3_f32 v7, v7, s32, v248
	v_fmamk_f32 v10, v50, 0x3cc80000, v247
	v_fmamk_f32 v11, v51, 0x3cc80000, v247
	v_fmamk_f32 v12, v48, 0x3cc80000, v247
	v_fmamk_f32 v13, v49, 0x3cc80000, v247
	v_perm_b32 v3, v8, v3, s59
	v_perm_b32 v6, v7, v6, s60
	v_med3_f32 v7, v12, s32, v248
	v_med3_f32 v8, v13, s32, v248
	v_med3_f32 v9, v10, s32, v248
	v_med3_f32 v10, v11, s32, v248
	v_perm_b32 v7, v8, v7, s59
	v_perm_b32 v8, v10, v9, s60
	v_bitop3_b32 v6, v3, s61, v6 bitop3:0x36
	v_bitop3_b32 v7, v7, s61, v8 bitop3:0x36
	global_store_dwordx2 v[4:5], v[6:7], off offset:128
	v_fmamk_f32 v4, v46, 0x3cc80000, v247
	v_fmamk_f32 v5, v47, 0x3cc80000, v247
	v_fmamk_f32 v6, v44, 0x3cc80000, v247
	v_fmamk_f32 v7, v45, 0x3cc80000, v247
	v_med3_f32 v4, v4, s32, v248
	v_med3_f32 v6, v6, s32, v248
	v_med3_f32 v7, v7, s32, v248
	v_med3_f32 v5, v5, s32, v248
	v_add_u32_e32 v2, 0xb0, v2
	v_fmamk_f32 v8, v42, 0x3cc80000, v247
	v_fmamk_f32 v9, v43, 0x3cc80000, v247
	v_fmamk_f32 v10, v40, 0x3cc80000, v247
	v_fmamk_f32 v11, v41, 0x3cc80000, v247
	v_ashrrev_i32_e32 v3, 31, v2
	v_perm_b32 v6, v7, v6, s59
	v_perm_b32 v4, v5, v4, s60
	v_med3_f32 v5, v10, s32, v248
	v_med3_f32 v7, v11, s32, v248
	v_med3_f32 v8, v8, s32, v248
	v_med3_f32 v9, v9, s32, v248
	v_lshlrev_b64 v[2:3], 11, v[2:3]
	v_perm_b32 v5, v7, v5, s59
	v_perm_b32 v7, v9, v8, s60
	v_lshl_add_u64 v[2:3], s[16:17], 0, v[2:3]
	v_bitop3_b32 v4, v6, s61, v4 bitop3:0x36
	v_bitop3_b32 v5, v5, s61, v7 bitop3:0x36
	v_lshl_add_u64 v[0:1], v[2:3], 0, v[0:1]
	global_store_dwordx2 v[0:1], v[4:5], off
	v_fmamk_f32 v2, v38, 0x3cc80000, v247
	v_fmamk_f32 v3, v39, 0x3cc80000, v247
	v_fmamk_f32 v4, v36, 0x3cc80000, v247
	v_fmamk_f32 v5, v37, 0x3cc80000, v247
	v_med3_f32 v2, v2, s32, v248
	v_med3_f32 v4, v4, s32, v248
	v_med3_f32 v5, v5, s32, v248
	v_med3_f32 v3, v3, s32, v248
	v_fmamk_f32 v6, v34, 0x3cc80000, v247
	v_fmamk_f32 v7, v35, 0x3cc80000, v247
	v_fmamk_f32 v8, v32, 0x3cc80000, v247
	v_fmamk_f32 v9, v33, 0x3cc80000, v247
	v_perm_b32 v4, v5, v4, s59
	v_perm_b32 v2, v3, v2, s60
	v_med3_f32 v3, v8, s32, v248
	v_med3_f32 v5, v9, s32, v248
	v_med3_f32 v6, v6, s32, v248
	v_med3_f32 v7, v7, s32, v248
	v_perm_b32 v3, v5, v3, s59
	v_perm_b32 v5, v7, v6, s60
	v_bitop3_b32 v2, v4, s61, v2 bitop3:0x36
	v_bitop3_b32 v3, v3, s61, v5 bitop3:0x36
	s_and_b64 vcc, exec, s[2:3]
	s_mov_b64 s[2:3], -1
	global_store_dwordx2 v[0:1], v[2:3], off offset:128
	s_cbranch_vccnz .LBB0_4805
	s_andn2_b64 vcc, exec, s[14:15]
	s_cbranch_vccnz .LBB0_4804
	s_barrier
	s_branch .LBB0_4804
